# v6 + down-GEMM residual epilogue: 16 residual loads batched with counted vmcnt; MoBA gate kmean loads hoisted per block (4 round trips to 1)
# baseline (speedup 1.0000x reference)
; __device__ __forceinline__ float bflo(unsigned w) { return __uint_as_float(w << 16); }
; __device__ __forceinline__ float bfhi(unsigned w) { return __uint_as_float(w & 0xffff0000u); }
;     __device__ __forceinline__ void fused(f32x4 (&acc)[2][2][4][2], const Unit& u, int wr, int wc, int fr, int fq, LAS unsigned char* lds, int wid, int lane) const {
;     ...
;             const f32x4 g0 = *(const f32x4*)(gate + boff + col), g1 = *(const f32x4*)(gate + boff + col + 4);
;             if (xin32) {
; #pragma unroll
;                 for (int ai = 0; ai < 2; ++ai)
; #pragma unroll
;                     for (int m = 0; m < 4; ++m) {
;                         const float* xp = xin32 + (unsigned)((row0 + ai * 128 + m * 16) * DM + col);
;                         const f32x4 x0 = *(const f32x4*)xp, x1 = *(const f32x4*)(xp + 4);
;                         acc[ai][bj][m][0] = x0 + g0 * acc[ai][bj][m][0]; acc[ai][bj][m][1] = x1 + g1 * acc[ai][bj][m][1];
;                         asm volatile("" : "+v"(acc[ai][bj][m][0]), "+v"(acc[ai][bj][m][1]));
;                         if (m & 1) asm volatile("" ::: "memory");
;                     }
;             } else {
; #pragma unroll
;                 for (int ai = 0; ai < 2; ++ai)
; #pragma unroll
;                     for (int m = 0; m < 4; ++m) {
;                         const u32x4 xw = *(const u32x4*)(xin16 + (unsigned)((row0 + ai * 128 + m * 16) * DM + col));
;                         const f32x4 x0 = (f32x4){bflo(xw.x), bfhi(xw.x), bflo(xw.y), bfhi(xw.y)}, x1 = (f32x4){bflo(xw.z), bfhi(xw.z), bflo(xw.w), bfhi(xw.w)};
;                         acc[ai][bj][m][0] = x0 + g0 * acc[ai][bj][m][0]; acc[ai][bj][m][1] = x1 + g1 * acc[ai][bj][m][1];
;                         asm volatile("" : "+v"(acc[ai][bj][m][0]), "+v"(acc[ai][bj][m][1]));
;                     }
.LBB0_144:
	s_lshl_b32 s12, s22, 8
	s_add_i32 s0, s12, s35
	v_lshrrev_b32_e32 v64, 1, v236
	v_or_b32_e32 v130, s0, v144
	s_lshr_b32 s0, s22, 3
	v_and_b32_e32 v64, 24, v64
	s_mul_i32 s80, s0, 0x1800
	v_lshl_or_b32 v64, s25, 5, v64
	s_lshl_b64 s[2:3], s[80:81], 2
	v_readlane_b32 s0, v255, 48
	v_lshl_or_b32 v154, s8, 8, v64
	s_add_u32 s0, s0, s2
	v_readlane_b32 s1, v255, 49
	s_addc_u32 s1, s1, s3
	v_ashrrev_i32_e32 v155, 31, v154
	v_lshlrev_b32_e32 v141, 10, v130
	v_lshl_add_u64 v[130:131], v[154:155], 2, s[0:1]
	s_mov_b64 s[0:1], 0x5000
	v_lshl_add_u64 v[138:139], v[130:131], 0, s[0:1]
	s_movk_i32 s0, 0x5000
	v_add_co_u32_e32 v130, vcc, s0, v130
	v_add_u32_e32 v64, v141, v154
	s_nop 0
	v_addc_co_u32_e32 v131, vcc, 0, v131, vcc
	v_lshl_add_u64 v[142:143], v[64:65], 1, s[36:37]
	s_barrier
	global_load_dwordx4 v[134:137], v[130:131], off
	s_nop 0
	global_load_dwordx4 v[130:133], v[138:139], off offset:16
	v_lshlrev_b32_e32 v210, 1, v64
	global_load_dwordx4 v[164:167], v210, s[36:37]
	global_load_dwordx4 v[196:199], v210, s[36:37] offset:256
	v_add_u32_e32 v210, 0x8000, v210
	global_load_dwordx4 v[168:171], v210, s[36:37]
	global_load_dwordx4 v[200:203], v210, s[36:37] offset:256
	v_add_u32_e32 v210, 0x8000, v210
	global_load_dwordx4 v[172:175], v210, s[36:37]
	global_load_dwordx4 v[206:209], v210, s[36:37] offset:256
	v_add_u32_e32 v210, 0x8000, v210
	global_load_dwordx4 v[176:179], v210, s[36:37]
	global_load_dwordx4 v[214:217], v210, s[36:37] offset:256
	v_add_u32_e32 v210, 0x28000, v210
	global_load_dwordx4 v[180:183], v210, s[36:37]
	global_load_dwordx4 v[218:221], v210, s[36:37] offset:256
	v_add_u32_e32 v210, 0x8000, v210
	global_load_dwordx4 v[184:187], v210, s[36:37]
	global_load_dwordx4 v[222:225], v210, s[36:37] offset:256
	v_add_u32_e32 v210, 0x8000, v210
	v_mov_b32_e32 v211, v210
	global_load_dwordx4 v[188:191], v210, s[36:37]
	v_add_u32_e32 v210, 0x8000, v210
	global_load_dwordx4 v[192:195], v210, s[36:37]
	v_or_b32_e32 v159, 0x80, v154
	v_and_b32_e32 v140, 63, v236
	s_lshl_b32 s0, s25, 2
	v_cmp_gt_u32_e32 vcc, 16, v140
	s_add_i32 s4, s0, 0
	s_waitcnt vmcnt(13) lgkmcnt(0)
	v_lshlrev_b32_e32 v142, 16, v164
	v_and_b32_e32 v143, 0xffff0000, v164
	v_lshlrev_b32_e32 v146, 16, v165
	v_and_b32_e32 v147, 0xffff0000, v165
	v_lshlrev_b32_e32 v150, 16, v166
	v_and_b32_e32 v151, 0xffff0000, v166
	v_lshlrev_b32_e32 v148, 16, v167
	v_and_b32_e32 v149, 0xffff0000, v167
	global_load_dwordx4 v[164:167], v211, s[36:37] offset:256
	v_pk_fma_f32 v[32:33], v[32:33], v[134:135], v[142:143]
	v_add_u32_e32 v142, 0x4000, v64
	v_mov_b32_e32 v143, v65
	v_pk_fma_f32 v[34:35], v[34:35], v[136:137], v[146:147]
	v_pk_fma_f32 v[38:39], v[38:39], v[132:133], v[148:149]
	v_pk_fma_f32 v[36:37], v[36:37], v[130:131], v[150:151]
	v_lshl_add_u64 v[142:143], v[142:143], 1, s[36:37]
	s_waitcnt vmcnt(12) lgkmcnt(0)
	v_lshlrev_b32_e32 v142, 16, v168
	v_and_b32_e32 v143, 0xffff0000, v168
	v_lshlrev_b32_e32 v146, 16, v169
	v_and_b32_e32 v147, 0xffff0000, v169
	v_lshlrev_b32_e32 v150, 16, v170
	v_and_b32_e32 v151, 0xffff0000, v170
	v_lshlrev_b32_e32 v148, 16, v171
	v_and_b32_e32 v149, 0xffff0000, v171
	global_load_dwordx4 v[168:171], v210, s[36:37] offset:256
	v_pk_fma_f32 v[48:49], v[48:49], v[134:135], v[142:143]
	v_add_u32_e32 v142, 0x8000, v64
	v_mov_b32_e32 v143, v65
	v_pk_fma_f32 v[50:51], v[50:51], v[136:137], v[146:147]
	v_pk_fma_f32 v[54:55], v[54:55], v[132:133], v[148:149]
	v_pk_fma_f32 v[52:53], v[52:53], v[130:131], v[150:151]
	v_lshl_add_u64 v[142:143], v[142:143], 1, s[36:37]
	s_waitcnt vmcnt(11) lgkmcnt(0)
	v_lshlrev_b32_e32 v142, 16, v172
	v_and_b32_e32 v143, 0xffff0000, v172
	v_lshlrev_b32_e32 v146, 16, v173
	v_and_b32_e32 v147, 0xffff0000, v173
	v_lshlrev_b32_e32 v150, 16, v174
	v_and_b32_e32 v151, 0xffff0000, v174
	v_lshlrev_b32_e32 v148, 16, v175
	v_and_b32_e32 v149, 0xffff0000, v175
	v_pk_fma_f32 v[56:57], v[56:57], v[134:135], v[142:143]
	v_add_u32_e32 v142, 0xc000, v64
	v_mov_b32_e32 v143, v65
	v_pk_fma_f32 v[58:59], v[58:59], v[136:137], v[146:147]
	v_pk_fma_f32 v[62:63], v[62:63], v[132:133], v[148:149]
	v_pk_fma_f32 v[60:61], v[60:61], v[130:131], v[150:151]
	v_lshl_add_u64 v[142:143], v[142:143], 1, s[36:37]
	s_waitcnt vmcnt(9) lgkmcnt(0)
	v_lshlrev_b32_e32 v142, 16, v176
	v_and_b32_e32 v143, 0xffff0000, v176
	v_lshlrev_b32_e32 v146, 16, v177
	v_and_b32_e32 v147, 0xffff0000, v177
	v_lshlrev_b32_e32 v150, 16, v178
	v_and_b32_e32 v151, 0xffff0000, v178
	v_lshlrev_b32_e32 v148, 16, v179
	v_and_b32_e32 v149, 0xffff0000, v179
	v_pk_fma_f32 v[74:75], v[74:75], v[134:135], v[142:143]
	v_add_u32_e32 v142, 0x20000, v64
	v_mov_b32_e32 v143, v65
	v_pk_fma_f32 v[76:77], v[76:77], v[136:137], v[146:147]
	v_pk_fma_f32 v[80:81], v[80:81], v[132:133], v[148:149]
	v_pk_fma_f32 v[78:79], v[78:79], v[130:131], v[150:151]
	v_lshl_add_u64 v[142:143], v[142:143], 1, s[36:37]
	s_waitcnt vmcnt(7) lgkmcnt(0)
	v_lshlrev_b32_e32 v142, 16, v180
	v_and_b32_e32 v143, 0xffff0000, v180
	v_lshlrev_b32_e32 v146, 16, v181
	v_and_b32_e32 v147, 0xffff0000, v181
	v_lshlrev_b32_e32 v150, 16, v182
	v_and_b32_e32 v151, 0xffff0000, v182
	v_lshlrev_b32_e32 v148, 16, v183
	v_and_b32_e32 v149, 0xffff0000, v183
	v_pk_fma_f32 v[82:83], v[82:83], v[134:135], v[142:143]
	v_add_u32_e32 v142, 0x24000, v64
	v_mov_b32_e32 v143, v65
	v_pk_fma_f32 v[84:85], v[84:85], v[136:137], v[146:147]
	v_pk_fma_f32 v[88:89], v[88:89], v[132:133], v[148:149]
	v_pk_fma_f32 v[86:87], v[86:87], v[130:131], v[150:151]
	v_lshl_add_u64 v[142:143], v[142:143], 1, s[36:37]
	s_waitcnt vmcnt(5) lgkmcnt(0)
; __device__ __forceinline__ float bflo(unsigned w) { return __uint_as_float(w << 16); }
; __device__ __forceinline__ float bfhi(unsigned w) { return __uint_as_float(w & 0xffff0000u); }
;     __device__ __forceinline__ void fused(f32x4 (&acc)[2][2][4][2], const Unit& u, int wr, int wc, int fr, int fq, LAS unsigned char* lds, int wid, int lane) const {
;     ...
; #pragma unroll
;                 for (int ai = 0; ai < 2; ++ai)
; #pragma unroll
;                     for (int m = 0; m < 4; ++m) {
;                         const u32x4 xw = *(const u32x4*)(xin16 + (unsigned)((row0 + ai * 128 + m * 16) * DM + col));
;                         const f32x4 x0 = (f32x4){bflo(xw.x), bfhi(xw.x), bflo(xw.y), bfhi(xw.y)}, x1 = (f32x4){bflo(xw.z), bfhi(xw.z), bflo(xw.w), bfhi(xw.w)};
;                         acc[ai][bj][m][0] = x0 + g0 * acc[ai][bj][m][0]; acc[ai][bj][m][1] = x1 + g1 * acc[ai][bj][m][1];
;                         asm volatile("" : "+v"(acc[ai][bj][m][0]), "+v"(acc[ai][bj][m][1]));
;                     }
	v_lshlrev_b32_e32 v142, 16, v184
	v_and_b32_e32 v143, 0xffff0000, v184
	v_lshlrev_b32_e32 v146, 16, v185
	v_and_b32_e32 v147, 0xffff0000, v185
	v_lshlrev_b32_e32 v150, 16, v186
	v_and_b32_e32 v151, 0xffff0000, v186
	v_lshlrev_b32_e32 v148, 16, v187
	v_and_b32_e32 v149, 0xffff0000, v187
	v_pk_fma_f32 v[90:91], v[90:91], v[134:135], v[142:143]
	v_add_u32_e32 v142, 0x28000, v64
	v_mov_b32_e32 v143, v65
	v_pk_fma_f32 v[92:93], v[92:93], v[136:137], v[146:147]
	v_pk_fma_f32 v[96:97], v[96:97], v[132:133], v[148:149]
	v_pk_fma_f32 v[94:95], v[94:95], v[130:131], v[150:151]
	v_lshl_add_u64 v[142:143], v[142:143], 1, s[36:37]
	v_add_u32_e32 v64, 0x2c000, v64
	s_waitcnt vmcnt(3) lgkmcnt(0)
	v_lshlrev_b32_e32 v142, 16, v188
	v_and_b32_e32 v143, 0xffff0000, v188
	v_lshlrev_b32_e32 v146, 16, v189
	v_and_b32_e32 v147, 0xffff0000, v189
	v_lshlrev_b32_e32 v150, 16, v190
	v_and_b32_e32 v151, 0xffff0000, v190
	v_lshlrev_b32_e32 v148, 16, v191
	v_and_b32_e32 v149, 0xffff0000, v191
	v_pk_fma_f32 v[116:117], v[116:117], v[136:137], v[146:147]
	v_pk_fma_f32 v[114:115], v[114:115], v[134:135], v[142:143]
	v_pk_fma_f32 v[120:121], v[120:121], v[132:133], v[148:149]
	v_pk_fma_f32 v[118:119], v[118:119], v[130:131], v[150:151]
	v_lshl_add_u64 v[142:143], v[64:65], 1, s[36:37]
	v_add_u32_e32 v64, v141, v159
	s_waitcnt vmcnt(2) lgkmcnt(0)
	v_lshlrev_b32_e32 v142, 16, v192
	v_and_b32_e32 v143, 0xffff0000, v192
	v_lshlrev_b32_e32 v146, 16, v193
	v_and_b32_e32 v147, 0xffff0000, v193
	v_lshlrev_b32_e32 v150, 16, v194
	v_and_b32_e32 v151, 0xffff0000, v194
	v_lshlrev_b32_e32 v148, 16, v195
	v_and_b32_e32 v149, 0xffff0000, v195
	v_pk_fma_f32 v[124:125], v[124:125], v[136:137], v[146:147]
	v_pk_fma_f32 v[122:123], v[122:123], v[134:135], v[142:143]
	v_pk_fma_f32 v[128:129], v[128:129], v[132:133], v[148:149]
	v_pk_fma_f32 v[126:127], v[126:127], v[130:131], v[150:151]
	s_nop 0
	flat_load_dwordx4 v[134:137], v[138:139] offset:512
	flat_load_dwordx4 v[130:133], v[138:139] offset:528
	v_lshl_add_u64 v[138:139], v[64:65], 1, s[36:37]
	s_waitcnt vmcnt(0) lgkmcnt(0)
	v_lshlrev_b32_e32 v138, 16, v196
	v_and_b32_e32 v139, 0xffff0000, v196
	v_lshlrev_b32_e32 v142, 16, v197
	v_and_b32_e32 v143, 0xffff0000, v197
	v_lshlrev_b32_e32 v146, 16, v198
	v_and_b32_e32 v147, 0xffff0000, v198
	v_lshlrev_b32_e32 v148, 16, v199
	v_and_b32_e32 v149, 0xffff0000, v199
	v_pk_fma_f32 v[106:107], v[106:107], v[134:135], v[138:139]
	v_add_u32_e32 v138, 0x4000, v64
	v_mov_b32_e32 v139, v65
	v_pk_fma_f32 v[108:109], v[108:109], v[136:137], v[142:143]
	v_pk_fma_f32 v[112:113], v[112:113], v[132:133], v[148:149]
	v_pk_fma_f32 v[110:111], v[110:111], v[130:131], v[146:147]
	v_lshl_add_u64 v[138:139], v[138:139], 1, s[36:37]
	s_waitcnt vmcnt(0) lgkmcnt(0)
	v_lshlrev_b32_e32 v138, 16, v200
	v_and_b32_e32 v139, 0xffff0000, v200
	v_lshlrev_b32_e32 v142, 16, v201
	v_and_b32_e32 v143, 0xffff0000, v201
	v_lshlrev_b32_e32 v146, 16, v202
	v_and_b32_e32 v147, 0xffff0000, v202
	v_lshlrev_b32_e32 v148, 16, v203
	v_and_b32_e32 v149, 0xffff0000, v203
	v_pk_fma_f32 v[102:103], v[102:103], v[134:135], v[138:139]
	v_add_u32_e32 v138, 0x8000, v64
	v_mov_b32_e32 v139, v65
	v_pk_fma_f32 v[104:105], v[104:105], v[136:137], v[142:143]
	v_pk_fma_f32 v[100:101], v[100:101], v[132:133], v[148:149]
	v_pk_fma_f32 v[98:99], v[98:99], v[130:131], v[146:147]
	v_lshl_add_u64 v[138:139], v[138:139], 1, s[36:37]
	s_waitcnt vmcnt(0) lgkmcnt(0)
	v_lshlrev_b32_e32 v138, 16, v206
	v_and_b32_e32 v139, 0xffff0000, v206
	v_lshlrev_b32_e32 v142, 16, v207
	v_and_b32_e32 v143, 0xffff0000, v207
	v_lshlrev_b32_e32 v146, 16, v208
	v_and_b32_e32 v147, 0xffff0000, v208
	v_lshlrev_b32_e32 v148, 16, v209
	v_and_b32_e32 v149, 0xffff0000, v209
	v_pk_fma_f32 v[70:71], v[70:71], v[134:135], v[138:139]
	v_add_u32_e32 v138, 0xc000, v64
	v_mov_b32_e32 v139, v65
	v_pk_fma_f32 v[72:73], v[72:73], v[136:137], v[142:143]
	v_pk_fma_f32 v[68:69], v[68:69], v[132:133], v[148:149]
	v_pk_fma_f32 v[66:67], v[66:67], v[130:131], v[146:147]
	v_lshl_add_u64 v[138:139], v[138:139], 1, s[36:37]
	s_waitcnt vmcnt(0) lgkmcnt(0)
	v_lshlrev_b32_e32 v138, 16, v214
	v_and_b32_e32 v139, 0xffff0000, v214
	v_lshlrev_b32_e32 v142, 16, v215
	v_and_b32_e32 v143, 0xffff0000, v215
	v_lshlrev_b32_e32 v146, 16, v216
	v_and_b32_e32 v147, 0xffff0000, v216
	v_lshlrev_b32_e32 v148, 16, v217
	v_and_b32_e32 v149, 0xffff0000, v217
	v_pk_fma_f32 v[44:45], v[44:45], v[134:135], v[138:139]
	v_add_u32_e32 v138, 0x20000, v64
	v_mov_b32_e32 v139, v65
	v_pk_fma_f32 v[46:47], v[46:47], v[136:137], v[142:143]
	v_pk_fma_f32 v[42:43], v[42:43], v[132:133], v[148:149]
	v_pk_fma_f32 v[40:41], v[40:41], v[130:131], v[146:147]
	v_lshl_add_u64 v[138:139], v[138:139], 1, s[36:37]
	s_waitcnt vmcnt(0) lgkmcnt(0)
	v_lshlrev_b32_e32 v138, 16, v218
	v_and_b32_e32 v139, 0xffff0000, v218
	v_lshlrev_b32_e32 v142, 16, v219
	v_and_b32_e32 v143, 0xffff0000, v219
	v_lshlrev_b32_e32 v146, 16, v220
	v_and_b32_e32 v147, 0xffff0000, v220
	v_lshlrev_b32_e32 v148, 16, v221
	v_and_b32_e32 v149, 0xffff0000, v221
	v_pk_fma_f32 v[28:29], v[28:29], v[134:135], v[138:139]
	v_add_u32_e32 v138, 0x24000, v64
	v_mov_b32_e32 v139, v65
	v_pk_fma_f32 v[30:31], v[30:31], v[136:137], v[142:143]
	v_pk_fma_f32 v[26:27], v[26:27], v[132:133], v[148:149]
	v_pk_fma_f32 v[24:25], v[24:25], v[130:131], v[146:147]
	v_lshl_add_u64 v[138:139], v[138:139], 1, s[36:37]
	s_waitcnt vmcnt(0) lgkmcnt(0)
; __device__ __forceinline__ float bflo(unsigned w) { return __uint_as_float(w << 16); }
; __device__ __forceinline__ float bfhi(unsigned w) { return __uint_as_float(w & 0xffff0000u); }
; template <int K> __device__ __forceinline__ float swz_xor(float v) { return __int_as_float(__builtin_amdgcn_ds_swizzle(__float_as_int(v), (K << 10) | 0x1f)); }
; __device__ __forceinline__ float xor32_sum(float v) { auto rr = __builtin_amdgcn_permlane32_swap(__float_as_uint(v), __float_as_uint(v), false, false); return __uint_as_float(rr[0]) + __uint_as_float(rr[1]); }
;     __device__ __forceinline__ void run(const f32x4 (&v)[2][2][4][2], const Unit& u, int wr, int wc, int fr, int fq, LAS unsigned char* lds, int wid, int lane) const {
;     ...
; #pragma unroll
;         for (int ai = 0; ai < 2; ++ai)
; #pragma unroll
;             for (int m = 0; m < 4; ++m) {
;                 float q = 0.f;
; #pragma unroll
;                 for (int bj = 0; bj < 2; ++bj)
; #pragma unroll
;                     for (int n = 0; n < 2; ++n) { const f32x4 x = v[ai][bj][m][n]; q += (x[0] * x[0] + x[1] * x[1]) + (x[2] * x[2] + x[3] * x[3]); }
;                 q += swz_xor<16>(q); q = xor32_sum(q);
;                 if (fq == 0) P[(ai * 128 + wr * 64 + m * 16 + fr) * 4 + wc] = q;
;             }
;     __device__ __forceinline__ void fused(f32x4 (&acc)[2][2][4][2], const Unit& u, int wr, int wc, int fr, int fq, LAS unsigned char* lds, int wid, int lane) const {
;     ...
; #pragma unroll
;                 for (int ai = 0; ai < 2; ++ai)
; #pragma unroll
;                     for (int m = 0; m < 4; ++m) {
;                         const u32x4 xw = *(const u32x4*)(xin16 + (unsigned)((row0 + ai * 128 + m * 16) * DM + col));
;                         const f32x4 x0 = (f32x4){bflo(xw.x), bfhi(xw.x), bflo(xw.y), bfhi(xw.y)}, x1 = (f32x4){bflo(xw.z), bfhi(xw.z), bflo(xw.w), bfhi(xw.w)};
;                         acc[ai][bj][m][0] = x0 + g0 * acc[ai][bj][m][0]; acc[ai][bj][m][1] = x1 + g1 * acc[ai][bj][m][1];
;                         asm volatile("" : "+v"(acc[ai][bj][m][0]), "+v"(acc[ai][bj][m][1]));
;                     }
	v_lshlrev_b32_e32 v138, 16, v222
	v_and_b32_e32 v139, 0xffff0000, v222
	v_lshlrev_b32_e32 v142, 16, v223
	v_and_b32_e32 v143, 0xffff0000, v223
	v_lshlrev_b32_e32 v146, 16, v224
	v_and_b32_e32 v147, 0xffff0000, v224
	v_lshlrev_b32_e32 v148, 16, v225
	v_and_b32_e32 v149, 0xffff0000, v225
	v_pk_fma_f32 v[20:21], v[20:21], v[134:135], v[138:139]
	v_add_u32_e32 v138, 0x28000, v64
	v_mov_b32_e32 v139, v65
	v_pk_fma_f32 v[22:23], v[22:23], v[136:137], v[142:143]
	v_pk_fma_f32 v[18:19], v[18:19], v[132:133], v[148:149]
	v_pk_fma_f32 v[16:17], v[16:17], v[130:131], v[146:147]
	v_lshl_add_u64 v[138:139], v[138:139], 1, s[36:37]
	v_add_u32_e32 v64, 0x2c000, v64
	s_waitcnt vmcnt(0) lgkmcnt(0)
	v_lshlrev_b32_e32 v138, 16, v164
	v_and_b32_e32 v139, 0xffff0000, v164
	v_lshlrev_b32_e32 v142, 16, v165
	v_and_b32_e32 v143, 0xffff0000, v165
	v_lshlrev_b32_e32 v146, 16, v166
	v_and_b32_e32 v147, 0xffff0000, v166
	v_lshlrev_b32_e32 v148, 16, v167
	v_and_b32_e32 v149, 0xffff0000, v167
	v_pk_fma_f32 v[14:15], v[14:15], v[136:137], v[142:143]
	v_pk_fma_f32 v[12:13], v[12:13], v[134:135], v[138:139]
	v_pk_fma_f32 v[10:11], v[10:11], v[132:133], v[148:149]
	v_pk_fma_f32 v[8:9], v[8:9], v[130:131], v[146:147]
	v_lshl_add_u64 v[138:139], v[64:65], 1, s[36:37]
	v_mul_f32_e32 v64, v33, v33
	v_fmac_f32_e32 v64, v32, v32
	s_waitcnt vmcnt(0) lgkmcnt(0)
	v_lshlrev_b32_e32 v138, 16, v168
	v_and_b32_e32 v139, 0xffff0000, v168
	v_lshlrev_b32_e32 v142, 16, v169
	v_and_b32_e32 v143, 0xffff0000, v169
	v_lshlrev_b32_e32 v146, 16, v170
	v_and_b32_e32 v147, 0xffff0000, v170
	v_pk_fma_f32 v[0:1], v[0:1], v[130:131], v[146:147]
	v_mul_f32_e32 v130, v35, v35
	v_fmac_f32_e32 v130, v34, v34
	v_add_f32_e32 v64, v64, v130
	v_mul_f32_e32 v130, v37, v37
	v_mul_f32_e32 v131, v39, v39
	v_fmac_f32_e32 v130, v36, v36
	v_fmac_f32_e32 v131, v38, v38
	v_add_f32_e32 v130, v130, v131
	v_add_f32_e32 v64, v64, v130
	v_mul_f32_e32 v130, v107, v107
	v_mul_f32_e32 v131, v109, v109
	v_fmac_f32_e32 v130, v106, v106
	v_fmac_f32_e32 v131, v108, v108
	v_add_f32_e32 v130, v130, v131
	v_add_f32_e32 v64, v64, v130
	v_mul_f32_e32 v130, v111, v111
	v_mul_f32_e32 v131, v113, v113
	v_fmac_f32_e32 v130, v110, v110
	v_fmac_f32_e32 v131, v112, v112
	v_add_f32_e32 v130, v130, v131
	v_add_f32_e32 v64, v130, v64
	ds_swizzle_b32 v130, v64 offset:swizzle(SWAP,16)
	v_lshlrev_b32_e32 v148, 16, v171
	v_and_b32_e32 v149, 0xffff0000, v171
	v_pk_fma_f32 v[6:7], v[6:7], v[136:137], v[142:143]
	v_pk_fma_f32 v[4:5], v[4:5], v[134:135], v[138:139]
	v_pk_fma_f32 v[2:3], v[2:3], v[132:133], v[148:149]
	s_waitcnt lgkmcnt(0)
	v_add_f32_e32 v64, v64, v130
	v_mov_b32_e32 v130, v64
	s_nop 1
	v_permlane32_swap_b32_e32 v64, v130
	s_and_saveexec_b64 s[0:1], vcc
	s_lshl_b32 s5, s24, 10
	s_add_i32 s5, s4, s5
	v_lshl_add_u32 v131, v144, 4, s5
	v_add_f32_e32 v64, v64, v130
	ds_write_b32 v131, v64
	s_or_b64 exec, exec, s[0:1]
	v_mul_f32_e32 v64, v49, v49
	v_mul_f32_e32 v130, v51, v51
	v_fmac_f32_e32 v64, v48, v48
	v_fmac_f32_e32 v130, v50, v50
	v_add_f32_e32 v64, v64, v130
	v_mul_f32_e32 v130, v53, v53
	v_mul_f32_e32 v131, v55, v55
	v_fmac_f32_e32 v130, v52, v52
	v_fmac_f32_e32 v131, v54, v54
	v_add_f32_e32 v130, v130, v131
	v_add_f32_e32 v64, v64, v130
	v_mul_f32_e32 v130, v103, v103
	v_mul_f32_e32 v131, v105, v105
	v_fmac_f32_e32 v130, v102, v102
	v_fmac_f32_e32 v131, v104, v104
	v_add_f32_e32 v130, v130, v131
	v_add_f32_e32 v64, v64, v130
	v_mul_f32_e32 v130, v99, v99
	v_mul_f32_e32 v131, v101, v101
	v_fmac_f32_e32 v130, v98, v98
	v_fmac_f32_e32 v131, v100, v100
	v_add_f32_e32 v130, v130, v131
	v_add_f32_e32 v64, v130, v64
	ds_swizzle_b32 v130, v64 offset:swizzle(SWAP,16)
	s_waitcnt lgkmcnt(0)
	v_add_f32_e32 v64, v64, v130
	v_mov_b32_e32 v130, v64
	s_nop 1
	v_permlane32_swap_b32_e32 v64, v130
	s_and_saveexec_b64 s[0:1], vcc
	s_lshl_b32 s5, s24, 10
	s_add_i32 s5, s4, s5
	v_lshl_add_u32 v131, v144, 4, s5
	v_add_f32_e32 v64, v64, v130
	ds_write_b32 v131, v64 offset:256
	s_or_b64 exec, exec, s[0:1]
	v_mul_f32_e32 v64, v57, v57
	v_mul_f32_e32 v130, v59, v59
	v_fmac_f32_e32 v64, v56, v56
	v_fmac_f32_e32 v130, v58, v58
	v_add_f32_e32 v64, v64, v130
	v_mul_f32_e32 v130, v61, v61
	v_mul_f32_e32 v131, v63, v63
	v_fmac_f32_e32 v130, v60, v60
	v_fmac_f32_e32 v131, v62, v62
	v_add_f32_e32 v130, v130, v131
	v_add_f32_e32 v64, v64, v130
	v_mul_f32_e32 v130, v71, v71
	v_mul_f32_e32 v131, v73, v73
	v_fmac_f32_e32 v130, v70, v70
	v_fmac_f32_e32 v131, v72, v72
	v_add_f32_e32 v130, v130, v131
	v_add_f32_e32 v64, v64, v130
	v_mul_f32_e32 v130, v67, v67
	v_mul_f32_e32 v131, v69, v69
	v_fmac_f32_e32 v130, v66, v66
	v_fmac_f32_e32 v131, v68, v68
	v_add_f32_e32 v130, v130, v131
	v_add_f32_e32 v64, v130, v64
	ds_swizzle_b32 v130, v64 offset:swizzle(SWAP,16)
	s_waitcnt lgkmcnt(0)
	v_add_f32_e32 v64, v64, v130
	v_mov_b32_e32 v130, v64
	s_nop 1
	v_permlane32_swap_b32_e32 v64, v130
	s_and_saveexec_b64 s[0:1], vcc
	s_lshl_b32 s5, s24, 10
	s_add_i32 s5, s4, s5
	v_lshl_add_u32 v131, v144, 4, s5
	v_add_f32_e32 v64, v64, v130
	ds_write_b32 v131, v64 offset:512
	s_or_b64 exec, exec, s[0:1]
	v_mul_f32_e32 v64, v75, v75
	v_mul_f32_e32 v130, v77, v77
	v_fmac_f32_e32 v64, v74, v74
	v_fmac_f32_e32 v130, v76, v76
	v_add_f32_e32 v64, v64, v130
	v_mul_f32_e32 v130, v79, v79
	v_mul_f32_e32 v131, v81, v81
	v_fmac_f32_e32 v130, v78, v78
	v_fmac_f32_e32 v131, v80, v80
	v_add_f32_e32 v130, v130, v131
	v_add_f32_e32 v64, v64, v130
	v_mul_f32_e32 v130, v45, v45
	v_mul_f32_e32 v131, v47, v47
	v_fmac_f32_e32 v130, v44, v44
	v_fmac_f32_e32 v131, v46, v46
	v_add_f32_e32 v130, v130, v131
	v_add_f32_e32 v64, v64, v130
	v_mul_f32_e32 v130, v41, v41
	v_mul_f32_e32 v131, v43, v43
	v_fmac_f32_e32 v130, v40, v40
	v_fmac_f32_e32 v131, v42, v42
	v_add_f32_e32 v130, v130, v131
	v_add_f32_e32 v64, v130, v64
	ds_swizzle_b32 v130, v64 offset:swizzle(SWAP,16)
	s_waitcnt lgkmcnt(0)
; template <int K> __device__ __forceinline__ float swz_xor(float v) { return __int_as_float(__builtin_amdgcn_ds_swizzle(__float_as_int(v), (K << 10) | 0x1f)); }
; __device__ __forceinline__ float xor32_sum(float v) { auto rr = __builtin_amdgcn_permlane32_swap(__float_as_uint(v), __float_as_uint(v), false, false); return __uint_as_float(rr[0]) + __uint_as_float(rr[1]); }
;     __device__ __forceinline__ void run(const f32x4 (&v)[2][2][4][2], const Unit& u, int wr, int wc, int fr, int fq, LAS unsigned char* lds, int wid, int lane) const {
;     ...
;         for (int ai = 0; ai < 2; ++ai)
; #pragma unroll
;             for (int m = 0; m < 4; ++m) {
;                 float q = 0.f;
; #pragma unroll
;                 for (int bj = 0; bj < 2; ++bj)
; #pragma unroll
;                     for (int n = 0; n < 2; ++n) { const f32x4 x = v[ai][bj][m][n]; q += (x[0] * x[0] + x[1] * x[1]) + (x[2] * x[2] + x[3] * x[3]); }
;                 q += swz_xor<16>(q); q = xor32_sum(q);
;                 if (fq == 0) P[(ai * 128 + wr * 64 + m * 16 + fr) * 4 + wc] = q;
;             }
;         asm volatile("s_waitcnt lgkmcnt(0)" ::: "memory"); __builtin_amdgcn_s_barrier(); asm volatile("" ::: "memory");
;         const int row = wid * 32 + (lane & 31);
;         if (lane < 32) {
;             const float t = (P[row * 4 + 0] + P[row * 4 + 1]) + (P[row * 4 + 2] + P[row * 4 + 3]);
;             __hip_atomic_store(xbuf + ((size_t)(u.pm * 256 + row) * 4 + u.pn), __float_as_uint(t), __ATOMIC_RELAXED, __HIP_MEMORY_SCOPE_AGENT);
;         }
	v_add_f32_e32 v64, v64, v130
	v_mov_b32_e32 v130, v64
	s_nop 1
	v_permlane32_swap_b32_e32 v64, v130
	s_and_saveexec_b64 s[0:1], vcc
	s_lshl_b32 s5, s24, 10
	s_add_i32 s5, s4, s5
	v_lshl_add_u32 v131, v144, 4, s5
	v_add_f32_e32 v64, v64, v130
	ds_write_b32 v131, v64 offset:768
	s_or_b64 exec, exec, s[0:1]
	v_mul_f32_e32 v64, v83, v83
	v_mul_f32_e32 v130, v85, v85
	v_fmac_f32_e32 v64, v82, v82
	v_fmac_f32_e32 v130, v84, v84
	v_add_f32_e32 v64, v64, v130
	v_mul_f32_e32 v130, v87, v87
	v_mul_f32_e32 v131, v89, v89
	v_fmac_f32_e32 v130, v86, v86
	v_fmac_f32_e32 v131, v88, v88
	v_add_f32_e32 v130, v130, v131
	v_add_f32_e32 v64, v64, v130
	v_mul_f32_e32 v130, v29, v29
	v_mul_f32_e32 v131, v31, v31
	v_fmac_f32_e32 v130, v28, v28
	v_fmac_f32_e32 v131, v30, v30
	v_add_f32_e32 v130, v130, v131
	v_add_f32_e32 v64, v64, v130
	v_mul_f32_e32 v130, v25, v25
	v_mul_f32_e32 v131, v27, v27
	v_fmac_f32_e32 v130, v24, v24
	v_fmac_f32_e32 v131, v26, v26
	v_add_f32_e32 v130, v130, v131
	v_add_f32_e32 v64, v130, v64
	ds_swizzle_b32 v130, v64 offset:swizzle(SWAP,16)
	s_waitcnt lgkmcnt(0)
	v_add_f32_e32 v64, v64, v130
	v_mov_b32_e32 v130, v64
	s_nop 1
	v_permlane32_swap_b32_e32 v64, v130
	s_and_saveexec_b64 s[0:1], vcc
	s_lshl_b32 s5, s24, 10
	s_add_i32 s5, s4, s5
	v_lshl_add_u32 v131, v144, 4, s5
	v_add_f32_e32 v64, v64, v130
	ds_write_b32 v131, v64 offset:2048
	s_or_b64 exec, exec, s[0:1]
	v_mul_f32_e32 v64, v91, v91
	v_mul_f32_e32 v130, v93, v93
	v_fmac_f32_e32 v64, v90, v90
	v_fmac_f32_e32 v130, v92, v92
	v_add_f32_e32 v64, v64, v130
	v_mul_f32_e32 v130, v95, v95
	v_mul_f32_e32 v131, v97, v97
	v_fmac_f32_e32 v130, v94, v94
	v_fmac_f32_e32 v131, v96, v96
	v_add_f32_e32 v130, v130, v131
	v_add_f32_e32 v64, v64, v130
	v_mul_f32_e32 v130, v21, v21
	v_mul_f32_e32 v131, v23, v23
	v_fmac_f32_e32 v130, v20, v20
	v_fmac_f32_e32 v131, v22, v22
	v_add_f32_e32 v130, v130, v131
	v_add_f32_e32 v64, v64, v130
	v_mul_f32_e32 v130, v17, v17
	v_mul_f32_e32 v131, v19, v19
	v_fmac_f32_e32 v130, v16, v16
	v_fmac_f32_e32 v131, v18, v18
	v_add_f32_e32 v130, v130, v131
	v_add_f32_e32 v64, v130, v64
	ds_swizzle_b32 v130, v64 offset:swizzle(SWAP,16)
	s_waitcnt lgkmcnt(0)
	v_add_f32_e32 v64, v64, v130
	v_mov_b32_e32 v130, v64
	s_nop 1
	v_permlane32_swap_b32_e32 v64, v130
	s_and_saveexec_b64 s[0:1], vcc
	s_lshl_b32 s5, s24, 10
	s_add_i32 s5, s4, s5
	v_lshl_add_u32 v131, v144, 4, s5
	v_add_f32_e32 v64, v64, v130
	ds_write_b32 v131, v64 offset:2304
	s_or_b64 exec, exec, s[0:1]
	v_mul_f32_e32 v64, v115, v115
	v_mul_f32_e32 v130, v117, v117
	v_fmac_f32_e32 v64, v114, v114
	v_fmac_f32_e32 v130, v116, v116
	v_add_f32_e32 v64, v64, v130
	v_mul_f32_e32 v130, v119, v119
	v_mul_f32_e32 v131, v121, v121
	v_fmac_f32_e32 v130, v118, v118
	v_fmac_f32_e32 v131, v120, v120
	v_add_f32_e32 v130, v130, v131
	v_add_f32_e32 v64, v64, v130
	v_mul_f32_e32 v130, v13, v13
	v_mul_f32_e32 v131, v15, v15
	v_fmac_f32_e32 v130, v12, v12
	v_fmac_f32_e32 v131, v14, v14
	v_add_f32_e32 v130, v130, v131
	v_add_f32_e32 v64, v64, v130
	v_mul_f32_e32 v130, v9, v9
	v_mul_f32_e32 v131, v11, v11
	v_fmac_f32_e32 v130, v8, v8
	v_fmac_f32_e32 v131, v10, v10
	v_add_f32_e32 v130, v130, v131
	v_add_f32_e32 v64, v130, v64
	ds_swizzle_b32 v130, v64 offset:swizzle(SWAP,16)
	s_waitcnt lgkmcnt(0)
	v_add_f32_e32 v64, v64, v130
	v_mov_b32_e32 v130, v64
	s_nop 1
	v_permlane32_swap_b32_e32 v64, v130
	s_and_saveexec_b64 s[0:1], vcc
	s_lshl_b32 s5, s24, 10
	s_add_i32 s5, s4, s5
	v_lshl_add_u32 v131, v144, 4, s5
	v_add_f32_e32 v64, v64, v130
	ds_write_b32 v131, v64 offset:2560
	s_or_b64 exec, exec, s[0:1]
	v_mul_f32_e32 v64, v123, v123
	v_mul_f32_e32 v130, v125, v125
	v_fmac_f32_e32 v64, v122, v122
	v_fmac_f32_e32 v130, v124, v124
	v_add_f32_e32 v64, v64, v130
	v_mul_f32_e32 v130, v127, v127
	v_mul_f32_e32 v131, v129, v129
	v_fmac_f32_e32 v130, v126, v126
	v_fmac_f32_e32 v131, v128, v128
	v_add_f32_e32 v130, v130, v131
	v_add_f32_e32 v64, v64, v130
	v_mul_f32_e32 v130, v5, v5
	v_mul_f32_e32 v131, v7, v7
	v_fmac_f32_e32 v130, v4, v4
	v_fmac_f32_e32 v131, v6, v6
	v_add_f32_e32 v130, v130, v131
	v_add_f32_e32 v64, v64, v130
	v_mul_f32_e32 v130, v1, v1
	v_mul_f32_e32 v131, v3, v3
	v_fmac_f32_e32 v130, v0, v0
	v_fmac_f32_e32 v131, v2, v2
	v_add_f32_e32 v130, v130, v131
	v_add_f32_e32 v64, v130, v64
	ds_swizzle_b32 v130, v64 offset:swizzle(SWAP,16)
	s_waitcnt lgkmcnt(0)
	v_add_f32_e32 v64, v64, v130
	v_mov_b32_e32 v130, v64
	s_nop 1
	v_permlane32_swap_b32_e32 v64, v130
	s_and_saveexec_b64 s[0:1], vcc
	s_lshl_b32 s5, s24, 10
	s_add_i32 s4, s4, s5
	v_lshl_add_u32 v131, v144, 4, s4
	v_add_f32_e32 v64, v64, v130
	ds_write_b32 v131, v64 offset:2816
	s_or_b64 exec, exec, s[0:1]
	s_waitcnt lgkmcnt(0)
	s_barrier
	s_add_u32 s4, s82, 0x240000
	v_and_b32_e32 v64, 31, v236
	s_addc_u32 s5, s83, 0
	v_lshl_or_b32 v64, s9, 5, v64
	v_cmp_gt_u32_e64 s[0:1], 32, v140
	s_and_saveexec_b64 s[10:11], s[0:1]
	s_cbranch_execz .LBB0_162
	v_lshl_add_u32 v130, v64, 4, 0
	ds_read_b128 v[130:133], v130
	s_ashr_i32 s9, s8, 31
	s_waitcnt lgkmcnt(0)
	v_mov_b32_e32 v135, v132
	v_add_u32_e32 v132, s12, v64
	v_mov_b32_e32 v134, v131
	v_mov_b32_e32 v131, v133
	v_ashrrev_i32_e32 v133, 31, v132
	v_pk_add_f32 v[130:131], v[134:135], v[130:131]
	v_lshl_add_u64 v[132:133], v[132:133], 4, s[4:5]
	v_pk_add_f32 v[130:131], v[130:131], v[130:131] op_sel:[0,1] op_sel_hi:[1,0]
	v_lshl_add_u64 v[132:133], s[8:9], 2, v[132:133]
	flat_store_dword v[132:133], v130 sc1

; __device__ __forceinline__ void wg_unit_B(const bf16_t* qkv, const float* kmean, bf16_t* outB, int b, int hb, int qb, LAS unsigned char* lds, int wid, const WaveCtx& c, int tid) {
;     ...
;     float gate[7];
; #pragma unroll
;     for (int n = 0; n < 7; ++n) {
;         gate[n] = -INFINITY;
;         if (n < own) {
;             const float* km = kmean + (size_t)((b * 6 + hb) * 8 + n) * 64 + 8 * c.h;
;             float a = 0.f;
; #pragma unroll
;             for (int ks = 0; ks < 4; ++ks) {
;                 const f32x4 k0 = *(const f32x4*)(km + 16 * ks), k1 = *(const f32x4*)(km + 16 * ks + 4);
; #pragma unroll
; __device__ __forceinline__ void attn_phase(const Params& p, unsigned char* ws, int layer, LAS unsigned char* lds, const int tid, int rep) {
;     ...
;         for (;;) {
;             int t2 = tid; asm volatile("" : "+v"(t2));
;             const int lane = t2 & 63;
;             WaveCtx c; c.lane = lane; c.q = lane & 31; c.h = lane >> 5; c.vl = lds;
;             { const int i = lane & 15, qq = i >> 2, pp = i & 3, blk = (lane >> 4) & 1; c.troff = (4 * c.h + qq) * VROW + (16 * blk + 4 * pp) * 2; }
;             __syncthreads();
;             if (t2 == 0) *qw = atomicAdd(ctrB, 1u);
;             __syncthreads();
;             const unsigned u = (unsigned)__builtin_amdgcn_readfirstlane((int)*qw);
;             const unsigned ngu = (gridDim.x == 256) ? 128u : 0u;
;             if (u >= 384u + ngu) break;
;             if (u >= 192u && u < 192u + ngu) {
;                 pg8::StaticOrder so; so.init(M, NQKVG, 256, (int)(u - 192u));
;                 OneUnit S1; so.next(7, S1.u0);
;                 pg8::Gemm g{(const bf16_t*)(ws + WS_H), (const bf16_t*)(ws + WS_W + W_QKVG), M, NQKVG, DM};
;                 EpiQKVG E{(bf16_t*)(ws + WS_QKV), (bf16_t*)(ws + WS_GATES), p.b_gate + (size_t)layer * NG, (const float*)(ws + WS_COS), (const float*)(ws + WS_SIN), (float*)(ws + WS_KMEAN)};
;                 pg8::gemm_phase<EpiQKVG, OneUnit, false, GSP2>(lds, g, S1, E, t2);
;                 if (wid >= 4) __builtin_amdgcn_s_setprio(1);
;                 continue;
;             }
;             const unsigned ub = (u < 192u) ? u : u - ngu;
;             const int qb = 7 - (int)(ub / 48u), r2 = (int)(ub % 48u);
;             wg_unit_B(qkv, kmean, outB, r2 / 6, r2 % 6, qb, lds, wid, c, t2);
.LBB0_445:
	s_or_b64 exec, exec, s[2:3]
	v_mov_b32_e32 v0, s41
	s_waitcnt lgkmcnt(0)
	s_barrier
	ds_read_b32 v0, v0
	s_mov_b64 s[2:3], -1
	s_waitcnt lgkmcnt(0)
	v_readfirstlane_b32 s90, v0
	s_cmp_ge_u32 s90, s45
	s_cbranch_scc1 .LBB0_442
	s_cmpk_gt_u32 s90, 0xbf
	s_cselect_b64 s[2:3], -1, 0
	s_cmp_lt_u32 s90, s93
	s_cselect_b64 s[4:5], -1, 0
	s_and_b64 s[2:3], s[2:3], s[4:5]
	s_andn2_b64 vcc, exec, s[2:3]
	s_mov_b64 s[2:3], -1
	s_cbranch_vccz .LBB0_507
	s_cmpk_gt_u32 s90, 0xbf
	s_cselect_b32 s2, s46, 0
	s_sub_i32 s2, s90, s2
	s_mul_hi_u32 s3, s2, 0xaaaaaaab
	s_lshr_b32 s3, s3, 5
	s_sub_i32 s59, 7, s3
	s_mul_i32 s3, s3, 48
	s_sub_i32 s3, s2, s3
	s_and_b32 s4, s3, 0xff
	s_mulk_i32 s4, 0xab
	s_lshr_b32 s91, s4, 10
	s_mul_i32 s6, s91, 6
	s_sub_i32 s3, s3, s6
	s_lshl_b32 s20, s59, 8
	s_and_b32 s21, s3, 0xff
	s_add_i32 s20, s20, s34
	s_mul_i32 s3, s91, 0x1200000
	s_add_u32 s16, s84, s3
	v_and_b32_e32 v10, 31, v150
	s_addc_u32 s17, s85, 0
	v_or_b32_e32 v151, s20, v10
	v_mov_b64_e32 v[0:1], s[16:17]
	v_bfe_u32 v11, v150, 5, 1
	v_mad_i64_i32 v[0:1], s[4:5], v151, s71, v[0:1]
	s_lshl_b32 s80, s21, 7
	v_lshl_add_u64 v[0:1], v[0:1], 0, s[80:81]
	v_lshlrev_b32_e32 v4, 4, v11
	v_mov_b32_e32 v5, v65
	v_lshl_add_u64 v[0:1], v[0:1], 0, v[4:5]
	flat_load_dwordx4 v[114:117], v[0:1] offset:1536
	flat_load_dwordx4 v[118:121], v[0:1] offset:1568
	flat_load_dwordx4 v[122:125], v[0:1] offset:1600
	flat_load_dwordx4 v[126:129], v[0:1] offset:1632
	s_add_i32 s6, s6, s21
	s_lshl_b32 s3, s6, 9
	v_lshlrev_b32_e32 v64, 5, v11
	s_cmpk_lt_u32 s2, 0x150
	v_lshl_add_u64 v[6:7], s[48:49], 0, v[64:65]
	v_mov_b32_e32 v5, 0xff800000
	s_cselect_b64 s[4:5], -1, 0
	s_cmpk_gt_u32 s2, 0x14f
	v_mov_b32_e32 v12, 0xff800000
	s_cbranch_scc1 .LBB0_449
	s_lshl_b32 s80, s3, 2
	v_lshl_add_u64 v[8:9], v[6:7], 0, s[80:81]
	global_load_dwordx4 v[24:27], v[8:9], off
	global_load_dwordx4 v[28:31], v[8:9], off offset:16
	global_load_dwordx4 v[32:35], v[8:9], off offset:64
	global_load_dwordx4 v[36:39], v[8:9], off offset:80
	global_load_dwordx4 v[40:43], v[8:9], off offset:128
	global_load_dwordx4 v[44:47], v[8:9], off offset:144
	global_load_dwordx4 v[130:133], v[8:9], off offset:192
	global_load_dwordx4 v[134:137], v[8:9], off offset:208
	s_waitcnt vmcnt(6) lgkmcnt(0)
	v_lshlrev_b32_e32 v16, 16, v114
	v_fma_f32 v18, v24, v16, 0
	v_lshlrev_b32_e32 v0, 16, v116
	v_fmac_f32_e32 v18, v28, v0
	v_and_b32_e32 v0, 0xffff0000, v114
	v_fmac_f32_e32 v18, v25, v0
	v_and_b32_e32 v0, 0xffff0000, v116
	v_fmac_f32_e32 v18, v29, v0
	v_lshlrev_b32_e32 v0, 16, v115
	v_fmac_f32_e32 v18, v26, v0
	v_lshlrev_b32_e32 v0, 16, v117
	v_fmac_f32_e32 v18, v30, v0
	v_and_b32_e32 v0, 0xffff0000, v115
	v_fmac_f32_e32 v18, v27, v0
	v_and_b32_e32 v0, 0xffff0000, v117
	v_fmac_f32_e32 v18, v31, v0
	v_lshlrev_b32_e32 v16, 16, v118
	s_waitcnt vmcnt(4)
	v_fmac_f32_e32 v18, v32, v16
	v_lshlrev_b32_e32 v0, 16, v120
	v_fmac_f32_e32 v18, v36, v0
	v_and_b32_e32 v0, 0xffff0000, v118
	v_fmac_f32_e32 v18, v33, v0
	v_and_b32_e32 v0, 0xffff0000, v120
	v_fmac_f32_e32 v18, v37, v0
	v_lshlrev_b32_e32 v0, 16, v119
	v_fmac_f32_e32 v18, v34, v0
	v_lshlrev_b32_e32 v0, 16, v121
	v_fmac_f32_e32 v18, v38, v0
	v_and_b32_e32 v0, 0xffff0000, v119
	v_fmac_f32_e32 v18, v35, v0
	v_and_b32_e32 v0, 0xffff0000, v121
	v_fmac_f32_e32 v18, v39, v0
	v_lshlrev_b32_e32 v16, 16, v122
	s_waitcnt vmcnt(2)
	v_fmac_f32_e32 v18, v40, v16
	v_lshlrev_b32_e32 v0, 16, v124
	v_fmac_f32_e32 v18, v44, v0
	v_and_b32_e32 v0, 0xffff0000, v122
	v_fmac_f32_e32 v18, v41, v0
	v_and_b32_e32 v0, 0xffff0000, v124
	v_fmac_f32_e32 v18, v45, v0
	v_lshlrev_b32_e32 v0, 16, v123
	v_fmac_f32_e32 v18, v42, v0
	v_lshlrev_b32_e32 v0, 16, v125
	v_fmac_f32_e32 v18, v46, v0
	v_and_b32_e32 v0, 0xffff0000, v123
	v_fmac_f32_e32 v18, v43, v0
	v_and_b32_e32 v0, 0xffff0000, v125
	v_fmac_f32_e32 v18, v47, v0
	v_lshlrev_b32_e32 v9, 16, v126
	v_lshlrev_b32_e32 v8, 16, v128
	s_waitcnt vmcnt(0)
	v_mov_b32_e32 v0, v130
	v_mov_b32_e32 v1, v131
	v_mov_b32_e32 v2, v132
	v_mov_b32_e32 v3, v133
	v_mov_b32_e32 v12, v134
	v_mov_b32_e32 v13, v135
	v_mov_b32_e32 v14, v136
	v_mov_b32_e32 v15, v137
	v_mov_b32_e32 v17, v0
	v_mov_b32_e32 v16, v12
	v_pk_mul_f32 v[8:9], v[16:17], v[8:9]
	s_nop 0
	v_add_f32_e32 v0, v9, v18
	v_add_f32_e32 v12, v8, v0
	v_and_b32_e32 v9, 0xffff0000, v126
	v_and_b32_e32 v8, 0xffff0000, v128
	v_mov_b32_e32 v0, v13
	v_pk_mul_f32 v[0:1], v[0:1], v[8:9]
	v_mov_b32_e32 v8, v14
	v_add_f32_e32 v1, v1, v12
	v_add_f32_e32 v12, v0, v1
	v_lshlrev_b32_e32 v1, 16, v127
	v_lshlrev_b32_e32 v0, 16, v129
	v_mov_b32_e32 v9, v2
	v_pk_mul_f32 v[0:1], v[8:9], v[0:1]
	v_mov_b32_e32 v2, v15
	v_add_f32_e32 v1, v1, v12
	v_add_f32_e32 v8, v0, v1
	v_and_b32_e32 v1, 0xffff0000, v127
	v_and_b32_e32 v0, 0xffff0000, v129
	v_pk_mul_f32 v[0:1], v[2:3], v[0:1]
	s_nop 0
	v_add_f32_e32 v1, v1, v8
	v_add_f32_e32 v0, v0, v1
	v_mov_b32_e32 v1, v0
	s_nop 1
	v_permlane32_swap_b32_e32 v0, v1
	v_add_f32_e32 v12, v0, v1
; __device__ __forceinline__ float bf2f(unsigned short b) { return __uint_as_float((unsigned)b << 16); }
; __device__ __forceinline__ float xor32_sum(float v) { auto rr = __builtin_amdgcn_permlane32_swap(__float_as_uint(v), __float_as_uint(v), false, false); return __uint_as_float(rr[0]) + __uint_as_float(rr[1]); }
; __device__ __forceinline__ void wg_unit_B(const bf16_t* qkv, const float* kmean, bf16_t* outB, int b, int hb, int qb, LAS unsigned char* lds, int wid, const WaveCtx& c, int tid) {
;     ...
;     for (int n = 0; n < 7; ++n) {
;         gate[n] = -INFINITY;
;         if (n < own) {
;             const float* km = kmean + (size_t)((b * 6 + hb) * 8 + n) * 64 + 8 * c.h;
;             float a = 0.f;
; #pragma unroll
;             for (int ks = 0; ks < 4; ++ks) {
;                 const f32x4 k0 = *(const f32x4*)(km + 16 * ks), k1 = *(const f32x4*)(km + 16 * ks + 4);
; #pragma unroll
;                 for (int j = 0; j < 4; ++j) { a += bf2f((unsigned short)qf[ks][j]) * k0[j]; a += bf2f((unsigned short)qf[ks][4 + j]) * k1[j]; }
;             }
;             a = xor32_sum(a);
;             gate[n] = a;
;         }
;     }
.LBB0_449:
	s_cmpk_lt_u32 s2, 0x120
	s_cselect_b64 s[6:7], -1, 0
	s_cmpk_gt_u32 s2, 0x11f
	s_cbranch_scc1 .LBB0_451
	s_lshl_b32 s80, s3, 2
	v_lshl_add_u64 v[8:9], v[6:7], 0, s[80:81]
	global_load_dwordx4 v[24:27], v[8:9], off offset:256
	global_load_dwordx4 v[28:31], v[8:9], off offset:272
	global_load_dwordx4 v[32:35], v[8:9], off offset:320
	global_load_dwordx4 v[36:39], v[8:9], off offset:336
	global_load_dwordx4 v[40:43], v[8:9], off offset:384
	global_load_dwordx4 v[44:47], v[8:9], off offset:400
	global_load_dwordx4 v[130:133], v[8:9], off offset:448
	global_load_dwordx4 v[134:137], v[8:9], off offset:464
	s_waitcnt vmcnt(6) lgkmcnt(0)
	v_lshlrev_b32_e32 v5, 16, v114
	v_lshlrev_b32_e32 v13, 16, v118
	v_fma_f32 v5, v24, v5, 0
	v_lshlrev_b32_e32 v0, 16, v116
	v_fmac_f32_e32 v5, v28, v0
	v_and_b32_e32 v0, 0xffff0000, v114
	v_fmac_f32_e32 v5, v25, v0
	v_and_b32_e32 v0, 0xffff0000, v116
	v_fmac_f32_e32 v5, v29, v0
	v_lshlrev_b32_e32 v0, 16, v115
	v_fmac_f32_e32 v5, v26, v0
	v_lshlrev_b32_e32 v0, 16, v117
	v_fmac_f32_e32 v5, v30, v0
	v_and_b32_e32 v0, 0xffff0000, v115
	v_fmac_f32_e32 v5, v27, v0
	v_and_b32_e32 v0, 0xffff0000, v117
	v_fmac_f32_e32 v5, v31, v0
	s_waitcnt vmcnt(4)
	v_fmac_f32_e32 v5, v32, v13
	v_lshlrev_b32_e32 v0, 16, v120
	v_fmac_f32_e32 v5, v36, v0
	v_and_b32_e32 v0, 0xffff0000, v118
	v_fmac_f32_e32 v5, v33, v0
	v_and_b32_e32 v0, 0xffff0000, v120
	v_fmac_f32_e32 v5, v37, v0
	v_lshlrev_b32_e32 v0, 16, v119
	v_fmac_f32_e32 v5, v34, v0
	v_lshlrev_b32_e32 v0, 16, v121
	v_fmac_f32_e32 v5, v38, v0
	v_and_b32_e32 v0, 0xffff0000, v119
	v_fmac_f32_e32 v5, v35, v0
	v_and_b32_e32 v0, 0xffff0000, v121
	v_fmac_f32_e32 v5, v39, v0
	v_lshlrev_b32_e32 v13, 16, v122
	s_waitcnt vmcnt(2)
	v_fmac_f32_e32 v5, v40, v13
	v_lshlrev_b32_e32 v0, 16, v124
	v_fmac_f32_e32 v5, v44, v0
	v_and_b32_e32 v0, 0xffff0000, v122
	v_fmac_f32_e32 v5, v41, v0
	v_and_b32_e32 v0, 0xffff0000, v124
	v_fmac_f32_e32 v5, v45, v0
	v_lshlrev_b32_e32 v0, 16, v123
	v_fmac_f32_e32 v5, v42, v0
	v_lshlrev_b32_e32 v0, 16, v125
	v_fmac_f32_e32 v5, v46, v0
	v_and_b32_e32 v0, 0xffff0000, v123
	v_fmac_f32_e32 v5, v43, v0
	v_and_b32_e32 v0, 0xffff0000, v125
	v_fmac_f32_e32 v5, v47, v0
	v_lshlrev_b32_e32 v9, 16, v126
	v_lshlrev_b32_e32 v8, 16, v128
	s_waitcnt vmcnt(0)
	v_mov_b32_e32 v0, v130
	v_mov_b32_e32 v1, v131
	v_mov_b32_e32 v2, v132
	v_mov_b32_e32 v3, v133
	v_mov_b32_e32 v14, v134
	v_mov_b32_e32 v15, v135
	v_mov_b32_e32 v16, v136
	v_mov_b32_e32 v17, v137
	v_mov_b32_e32 v19, v0
	v_mov_b32_e32 v18, v14
	v_pk_mul_f32 v[8:9], v[18:19], v[8:9]
	s_nop 0
	v_add_f32_e32 v0, v9, v5
	v_add_f32_e32 v5, v8, v0
	v_and_b32_e32 v9, 0xffff0000, v126
	v_and_b32_e32 v8, 0xffff0000, v128
	v_mov_b32_e32 v0, v15
	v_pk_mul_f32 v[0:1], v[0:1], v[8:9]
	v_mov_b32_e32 v8, v16
	v_add_f32_e32 v1, v1, v5
	v_add_f32_e32 v5, v0, v1
	v_lshlrev_b32_e32 v1, 16, v127
	v_lshlrev_b32_e32 v0, 16, v129
	v_mov_b32_e32 v9, v2
	v_pk_mul_f32 v[0:1], v[8:9], v[0:1]
	v_mov_b32_e32 v2, v17
	v_add_f32_e32 v1, v1, v5
	v_add_f32_e32 v5, v0, v1
	v_and_b32_e32 v1, 0xffff0000, v127
	v_and_b32_e32 v0, 0xffff0000, v129
	v_pk_mul_f32 v[0:1], v[2:3], v[0:1]
	s_nop 0
	v_add_f32_e32 v1, v1, v5
	v_add_f32_e32 v0, v0, v1
	v_mov_b32_e32 v1, v0
	s_nop 1
	v_permlane32_swap_b32_e32 v0, v1
	v_add_f32_e32 v5, v0, v1
.LBB0_451:
	s_cmpk_lt_u32 s2, 0xf0
	v_mov_b32_e32 v13, 0xff800000
	s_cselect_b64 s[8:9], -1, 0
	s_cmpk_gt_u32 s2, 0xef
	v_mov_b32_e32 v14, 0xff800000
	s_cbranch_scc1 .LBB0_453
	s_lshl_b32 s80, s3, 2
	v_lshl_add_u64 v[8:9], v[6:7], 0, s[80:81]
	global_load_dwordx4 v[24:27], v[8:9], off offset:512
	global_load_dwordx4 v[28:31], v[8:9], off offset:528
	global_load_dwordx4 v[32:35], v[8:9], off offset:576
	global_load_dwordx4 v[36:39], v[8:9], off offset:592
	global_load_dwordx4 v[40:43], v[8:9], off offset:640
	global_load_dwordx4 v[44:47], v[8:9], off offset:656
	global_load_dwordx4 v[130:133], v[8:9], off offset:704
	global_load_dwordx4 v[134:137], v[8:9], off offset:720
	s_waitcnt vmcnt(6) lgkmcnt(0)
	v_lshlrev_b32_e32 v18, 16, v114
	v_fma_f32 v20, v24, v18, 0
	v_lshlrev_b32_e32 v0, 16, v116
	v_fmac_f32_e32 v20, v28, v0
	v_and_b32_e32 v0, 0xffff0000, v114
	v_fmac_f32_e32 v20, v25, v0
	v_and_b32_e32 v0, 0xffff0000, v116
	v_fmac_f32_e32 v20, v29, v0
	v_lshlrev_b32_e32 v0, 16, v115
	v_fmac_f32_e32 v20, v26, v0
	v_lshlrev_b32_e32 v0, 16, v117
	v_fmac_f32_e32 v20, v30, v0
	v_and_b32_e32 v0, 0xffff0000, v115
	v_fmac_f32_e32 v20, v27, v0
	v_and_b32_e32 v0, 0xffff0000, v117
	v_fmac_f32_e32 v20, v31, v0
	v_lshlrev_b32_e32 v18, 16, v118
	s_waitcnt vmcnt(4)
	v_fmac_f32_e32 v20, v32, v18
	v_lshlrev_b32_e32 v0, 16, v120
	v_fmac_f32_e32 v20, v36, v0
	v_and_b32_e32 v0, 0xffff0000, v118
	v_fmac_f32_e32 v20, v33, v0
	v_and_b32_e32 v0, 0xffff0000, v120
	v_fmac_f32_e32 v20, v37, v0
	v_lshlrev_b32_e32 v0, 16, v119
	v_fmac_f32_e32 v20, v34, v0
	v_lshlrev_b32_e32 v0, 16, v121
	v_fmac_f32_e32 v20, v38, v0
	v_and_b32_e32 v0, 0xffff0000, v119
	v_fmac_f32_e32 v20, v35, v0
	v_and_b32_e32 v0, 0xffff0000, v121
	v_fmac_f32_e32 v20, v39, v0
	v_lshlrev_b32_e32 v18, 16, v122
	s_waitcnt vmcnt(2)
	v_fmac_f32_e32 v20, v40, v18
	v_lshlrev_b32_e32 v0, 16, v124
	v_fmac_f32_e32 v20, v44, v0
	v_and_b32_e32 v0, 0xffff0000, v122
	v_fmac_f32_e32 v20, v41, v0
	v_and_b32_e32 v0, 0xffff0000, v124
	v_fmac_f32_e32 v20, v45, v0
	v_lshlrev_b32_e32 v0, 16, v123
	v_fmac_f32_e32 v20, v42, v0
	v_lshlrev_b32_e32 v0, 16, v125
	v_fmac_f32_e32 v20, v46, v0
	v_and_b32_e32 v0, 0xffff0000, v123
	v_fmac_f32_e32 v20, v43, v0
	v_and_b32_e32 v0, 0xffff0000, v125
	v_fmac_f32_e32 v20, v47, v0
	v_lshlrev_b32_e32 v9, 16, v126
	v_lshlrev_b32_e32 v8, 16, v128
	s_waitcnt vmcnt(0)
	v_mov_b32_e32 v0, v130
	v_mov_b32_e32 v1, v131
	v_mov_b32_e32 v2, v132
	v_mov_b32_e32 v3, v133
	v_mov_b32_e32 v14, v134
	v_mov_b32_e32 v15, v135
	v_mov_b32_e32 v16, v136
	v_mov_b32_e32 v17, v137
	v_mov_b32_e32 v19, v0
	v_mov_b32_e32 v18, v14
	v_pk_mul_f32 v[8:9], v[18:19], v[8:9]
	s_nop 0
	v_add_f32_e32 v0, v9, v20
	v_add_f32_e32 v14, v8, v0
	v_and_b32_e32 v9, 0xffff0000, v126
	v_and_b32_e32 v8, 0xffff0000, v128
	v_mov_b32_e32 v0, v15
	v_pk_mul_f32 v[0:1], v[0:1], v[8:9]
	v_mov_b32_e32 v8, v16
	v_add_f32_e32 v1, v1, v14
	v_add_f32_e32 v14, v0, v1
	v_lshlrev_b32_e32 v1, 16, v127
	v_lshlrev_b32_e32 v0, 16, v129
	v_mov_b32_e32 v9, v2
	v_pk_mul_f32 v[0:1], v[8:9], v[0:1]
	v_mov_b32_e32 v2, v17
	v_add_f32_e32 v1, v1, v14
	v_add_f32_e32 v8, v0, v1
	v_and_b32_e32 v1, 0xffff0000, v127
	v_and_b32_e32 v0, 0xffff0000, v129
	v_pk_mul_f32 v[0:1], v[2:3], v[0:1]
	s_nop 0
	v_add_f32_e32 v1, v1, v8
	v_add_f32_e32 v0, v0, v1
	v_mov_b32_e32 v1, v0
	s_nop 1
	v_permlane32_swap_b32_e32 v0, v1
	v_add_f32_e32 v14, v0, v1
; __device__ __forceinline__ float bf2f(unsigned short b) { return __uint_as_float((unsigned)b << 16); }
; __device__ __forceinline__ float xor32_sum(float v) { auto rr = __builtin_amdgcn_permlane32_swap(__float_as_uint(v), __float_as_uint(v), false, false); return __uint_as_float(rr[0]) + __uint_as_float(rr[1]); }
; __device__ __forceinline__ void wg_unit_B(const bf16_t* qkv, const float* kmean, bf16_t* outB, int b, int hb, int qb, LAS unsigned char* lds, int wid, const WaveCtx& c, int tid) {
;     ...
;     for (int n = 0; n < 7; ++n) {
;         gate[n] = -INFINITY;
;         if (n < own) {
;             const float* km = kmean + (size_t)((b * 6 + hb) * 8 + n) * 64 + 8 * c.h;
;             float a = 0.f;
; #pragma unroll
;             for (int ks = 0; ks < 4; ++ks) {
;                 const f32x4 k0 = *(const f32x4*)(km + 16 * ks), k1 = *(const f32x4*)(km + 16 * ks + 4);
; #pragma unroll
;                 for (int j = 0; j < 4; ++j) { a += bf2f((unsigned short)qf[ks][j]) * k0[j]; a += bf2f((unsigned short)qf[ks][4 + j]) * k1[j]; }
;             }
;             a = xor32_sum(a);
;             gate[n] = a;
;         }
;     }
.LBB0_453:
	s_cmpk_lt_u32 s2, 0xc0
	s_cselect_b64 s[10:11], -1, 0
	s_cmpk_gt_u32 s2, 0xbf
	s_cbranch_scc1 .LBB0_455
	s_lshl_b32 s80, s3, 2
	v_lshl_add_u64 v[8:9], v[6:7], 0, s[80:81]
	global_load_dwordx4 v[24:27], v[8:9], off offset:768
	global_load_dwordx4 v[28:31], v[8:9], off offset:784
	global_load_dwordx4 v[32:35], v[8:9], off offset:832
	global_load_dwordx4 v[36:39], v[8:9], off offset:848
	global_load_dwordx4 v[40:43], v[8:9], off offset:896
	global_load_dwordx4 v[44:47], v[8:9], off offset:912
	global_load_dwordx4 v[130:133], v[8:9], off offset:960
	global_load_dwordx4 v[134:137], v[8:9], off offset:976
	s_waitcnt vmcnt(6) lgkmcnt(0)
	v_lshlrev_b32_e32 v13, 16, v114
	v_lshlrev_b32_e32 v15, 16, v118
	v_fma_f32 v13, v24, v13, 0
	v_lshlrev_b32_e32 v0, 16, v116
	v_fmac_f32_e32 v13, v28, v0
	v_and_b32_e32 v0, 0xffff0000, v114
	v_fmac_f32_e32 v13, v25, v0
	v_and_b32_e32 v0, 0xffff0000, v116
	v_fmac_f32_e32 v13, v29, v0
	v_lshlrev_b32_e32 v0, 16, v115
	v_fmac_f32_e32 v13, v26, v0
	v_lshlrev_b32_e32 v0, 16, v117
	v_fmac_f32_e32 v13, v30, v0
	v_and_b32_e32 v0, 0xffff0000, v115
	v_fmac_f32_e32 v13, v27, v0
	v_and_b32_e32 v0, 0xffff0000, v117
	v_fmac_f32_e32 v13, v31, v0
	s_waitcnt vmcnt(4)
	v_fmac_f32_e32 v13, v32, v15
	v_lshlrev_b32_e32 v0, 16, v120
	v_fmac_f32_e32 v13, v36, v0
	v_and_b32_e32 v0, 0xffff0000, v118
	v_fmac_f32_e32 v13, v33, v0
	v_and_b32_e32 v0, 0xffff0000, v120
	v_fmac_f32_e32 v13, v37, v0
	v_lshlrev_b32_e32 v0, 16, v119
	v_fmac_f32_e32 v13, v34, v0
	v_lshlrev_b32_e32 v0, 16, v121
	v_fmac_f32_e32 v13, v38, v0
	v_and_b32_e32 v0, 0xffff0000, v119
	v_fmac_f32_e32 v13, v35, v0
	v_and_b32_e32 v0, 0xffff0000, v121
	v_fmac_f32_e32 v13, v39, v0
	v_lshlrev_b32_e32 v15, 16, v122
	s_waitcnt vmcnt(2)
	v_fmac_f32_e32 v13, v40, v15
	v_lshlrev_b32_e32 v0, 16, v124
	v_fmac_f32_e32 v13, v44, v0
	v_and_b32_e32 v0, 0xffff0000, v122
	v_fmac_f32_e32 v13, v41, v0
	v_and_b32_e32 v0, 0xffff0000, v124
	v_fmac_f32_e32 v13, v45, v0
	v_lshlrev_b32_e32 v0, 16, v123
	v_fmac_f32_e32 v13, v42, v0
	v_lshlrev_b32_e32 v0, 16, v125
	v_fmac_f32_e32 v13, v46, v0
	v_and_b32_e32 v0, 0xffff0000, v123
	v_fmac_f32_e32 v13, v43, v0
	v_and_b32_e32 v0, 0xffff0000, v125
	v_fmac_f32_e32 v13, v47, v0
	v_lshlrev_b32_e32 v9, 16, v126
	v_lshlrev_b32_e32 v8, 16, v128
	s_waitcnt vmcnt(0)
	v_mov_b32_e32 v0, v130
	v_mov_b32_e32 v1, v131
	v_mov_b32_e32 v2, v132
	v_mov_b32_e32 v3, v133
	v_mov_b32_e32 v16, v134
	v_mov_b32_e32 v17, v135
	v_mov_b32_e32 v18, v136
	v_mov_b32_e32 v19, v137
	v_mov_b32_e32 v21, v0
	v_mov_b32_e32 v20, v16
	v_pk_mul_f32 v[8:9], v[20:21], v[8:9]
	s_nop 0
	v_add_f32_e32 v0, v9, v13
	v_add_f32_e32 v13, v8, v0
	v_and_b32_e32 v9, 0xffff0000, v126
	v_and_b32_e32 v8, 0xffff0000, v128
	v_mov_b32_e32 v0, v17
	v_pk_mul_f32 v[0:1], v[0:1], v[8:9]
	v_mov_b32_e32 v8, v18
	v_add_f32_e32 v1, v1, v13
	v_add_f32_e32 v13, v0, v1
	v_lshlrev_b32_e32 v1, 16, v127
	v_lshlrev_b32_e32 v0, 16, v129
	v_mov_b32_e32 v9, v2
	v_pk_mul_f32 v[0:1], v[8:9], v[0:1]
	v_mov_b32_e32 v2, v19
	v_add_f32_e32 v1, v1, v13
	v_add_f32_e32 v8, v0, v1
	v_and_b32_e32 v1, 0xffff0000, v127
	v_and_b32_e32 v0, 0xffff0000, v129
	v_pk_mul_f32 v[0:1], v[2:3], v[0:1]
	s_nop 0
	v_add_f32_e32 v1, v1, v8
	v_add_f32_e32 v0, v0, v1
	v_mov_b32_e32 v1, v0
	s_nop 1
	v_permlane32_swap_b32_e32 v0, v1
	v_add_f32_e32 v13, v0, v1
.LBB0_455:
	s_cmpk_lt_u32 s2, 0x90
	v_mov_b32_e32 v15, 0xff800000
	s_cselect_b64 s[12:13], -1, 0
	s_cmpk_gt_u32 s2, 0x8f
	v_mov_b32_e32 v16, 0xff800000
	s_cbranch_scc1 .LBB0_457
	s_lshl_b32 s80, s3, 2
	v_lshl_add_u64 v[8:9], v[6:7], 0, s[80:81]
	global_load_dwordx4 v[24:27], v[8:9], off offset:1024
	global_load_dwordx4 v[28:31], v[8:9], off offset:1040
	global_load_dwordx4 v[32:35], v[8:9], off offset:1088
	global_load_dwordx4 v[36:39], v[8:9], off offset:1104
	global_load_dwordx4 v[40:43], v[8:9], off offset:1152
	global_load_dwordx4 v[44:47], v[8:9], off offset:1168
	global_load_dwordx4 v[130:133], v[8:9], off offset:1216
	global_load_dwordx4 v[134:137], v[8:9], off offset:1232
	s_waitcnt vmcnt(6) lgkmcnt(0)
	v_lshlrev_b32_e32 v20, 16, v114
	v_fma_f32 v22, v24, v20, 0
	v_lshlrev_b32_e32 v0, 16, v116
	v_fmac_f32_e32 v22, v28, v0
	v_and_b32_e32 v0, 0xffff0000, v114
	v_fmac_f32_e32 v22, v25, v0
	v_and_b32_e32 v0, 0xffff0000, v116
	v_fmac_f32_e32 v22, v29, v0
	v_lshlrev_b32_e32 v0, 16, v115
	v_fmac_f32_e32 v22, v26, v0
	v_lshlrev_b32_e32 v0, 16, v117
	v_fmac_f32_e32 v22, v30, v0
	v_and_b32_e32 v0, 0xffff0000, v115
	v_fmac_f32_e32 v22, v27, v0
	v_and_b32_e32 v0, 0xffff0000, v117
	v_fmac_f32_e32 v22, v31, v0
	v_lshlrev_b32_e32 v20, 16, v118
	s_waitcnt vmcnt(4)
	v_fmac_f32_e32 v22, v32, v20
	v_lshlrev_b32_e32 v0, 16, v120
	v_fmac_f32_e32 v22, v36, v0
	v_and_b32_e32 v0, 0xffff0000, v118
	v_fmac_f32_e32 v22, v33, v0
	v_and_b32_e32 v0, 0xffff0000, v120
	v_fmac_f32_e32 v22, v37, v0
	v_lshlrev_b32_e32 v0, 16, v119
	v_fmac_f32_e32 v22, v34, v0
	v_lshlrev_b32_e32 v0, 16, v121
	v_fmac_f32_e32 v22, v38, v0
	v_and_b32_e32 v0, 0xffff0000, v119
	v_fmac_f32_e32 v22, v35, v0
	v_and_b32_e32 v0, 0xffff0000, v121
	v_fmac_f32_e32 v22, v39, v0
	v_lshlrev_b32_e32 v20, 16, v122
	s_waitcnt vmcnt(2)
	v_fmac_f32_e32 v22, v40, v20
	v_lshlrev_b32_e32 v0, 16, v124
	v_fmac_f32_e32 v22, v44, v0
	v_and_b32_e32 v0, 0xffff0000, v122
	v_fmac_f32_e32 v22, v41, v0
	v_and_b32_e32 v0, 0xffff0000, v124
	v_fmac_f32_e32 v22, v45, v0
	v_lshlrev_b32_e32 v0, 16, v123
	v_fmac_f32_e32 v22, v42, v0
	v_lshlrev_b32_e32 v0, 16, v125
	v_fmac_f32_e32 v22, v46, v0
	v_and_b32_e32 v0, 0xffff0000, v123
	v_fmac_f32_e32 v22, v43, v0
	v_and_b32_e32 v0, 0xffff0000, v125
	v_fmac_f32_e32 v22, v47, v0
	v_lshlrev_b32_e32 v9, 16, v126
	v_lshlrev_b32_e32 v8, 16, v128
	s_waitcnt vmcnt(0)
	v_mov_b32_e32 v0, v130
	v_mov_b32_e32 v1, v131
	v_mov_b32_e32 v2, v132
	v_mov_b32_e32 v3, v133
	v_mov_b32_e32 v16, v134
	v_mov_b32_e32 v17, v135
	v_mov_b32_e32 v18, v136
	v_mov_b32_e32 v19, v137
	v_mov_b32_e32 v21, v0
	v_mov_b32_e32 v20, v16
	v_pk_mul_f32 v[8:9], v[20:21], v[8:9]
	s_nop 0
	v_add_f32_e32 v0, v9, v22
	v_add_f32_e32 v16, v8, v0
	v_and_b32_e32 v9, 0xffff0000, v126
	v_and_b32_e32 v8, 0xffff0000, v128
	v_mov_b32_e32 v0, v17
	v_pk_mul_f32 v[0:1], v[0:1], v[8:9]
	v_mov_b32_e32 v8, v18
	v_add_f32_e32 v1, v1, v16
	v_add_f32_e32 v16, v0, v1
	v_lshlrev_b32_e32 v1, 16, v127
	v_lshlrev_b32_e32 v0, 16, v129
	v_mov_b32_e32 v9, v2
	v_pk_mul_f32 v[0:1], v[8:9], v[0:1]
	v_mov_b32_e32 v2, v19
	v_add_f32_e32 v1, v1, v16
	v_add_f32_e32 v8, v0, v1
	v_and_b32_e32 v1, 0xffff0000, v127
	v_and_b32_e32 v0, 0xffff0000, v129
	v_pk_mul_f32 v[0:1], v[2:3], v[0:1]
	s_nop 0
	v_add_f32_e32 v1, v1, v8
	v_add_f32_e32 v0, v0, v1
	v_mov_b32_e32 v1, v0
	s_nop 1
	v_permlane32_swap_b32_e32 v0, v1
	v_add_f32_e32 v16, v0, v1
; __device__ __forceinline__ float bf2f(unsigned short b) { return __uint_as_float((unsigned)b << 16); }
; __device__ __forceinline__ float xor32_sum(float v) { auto rr = __builtin_amdgcn_permlane32_swap(__float_as_uint(v), __float_as_uint(v), false, false); return __uint_as_float(rr[0]) + __uint_as_float(rr[1]); }
; __device__ __forceinline__ void wg_unit_B(const bf16_t* qkv, const float* kmean, bf16_t* outB, int b, int hb, int qb, LAS unsigned char* lds, int wid, const WaveCtx& c, int tid) {
;     ...
;     for (int n = 0; n < 7; ++n) {
;         gate[n] = -INFINITY;
;         if (n < own) {
;             const float* km = kmean + (size_t)((b * 6 + hb) * 8 + n) * 64 + 8 * c.h;
;             float a = 0.f;
; #pragma unroll
;             for (int ks = 0; ks < 4; ++ks) {
;                 const f32x4 k0 = *(const f32x4*)(km + 16 * ks), k1 = *(const f32x4*)(km + 16 * ks + 4);
; #pragma unroll
;                 for (int j = 0; j < 4; ++j) { a += bf2f((unsigned short)qf[ks][j]) * k0[j]; a += bf2f((unsigned short)qf[ks][4 + j]) * k1[j]; }
;             }
;             a = xor32_sum(a);
;             gate[n] = a;
;         }
;     }
.LBB0_457:
	s_cmpk_lt_u32 s2, 0x60
	s_cselect_b64 s[14:15], -1, 0
	s_cmpk_gt_u32 s2, 0x5f
	s_cbranch_scc1 .LBB0_459
	s_lshl_b32 s80, s3, 2
	v_lshl_add_u64 v[8:9], v[6:7], 0, s[80:81]
	global_load_dwordx4 v[24:27], v[8:9], off offset:1280
	global_load_dwordx4 v[28:31], v[8:9], off offset:1296
	global_load_dwordx4 v[32:35], v[8:9], off offset:1344
	global_load_dwordx4 v[36:39], v[8:9], off offset:1360
	global_load_dwordx4 v[40:43], v[8:9], off offset:1408
	global_load_dwordx4 v[44:47], v[8:9], off offset:1424
	global_load_dwordx4 v[130:133], v[8:9], off offset:1472
	global_load_dwordx4 v[134:137], v[8:9], off offset:1488
	s_waitcnt vmcnt(6) lgkmcnt(0)
	v_lshlrev_b32_e32 v15, 16, v114
	v_lshlrev_b32_e32 v17, 16, v118
	v_fma_f32 v15, v24, v15, 0
	v_lshlrev_b32_e32 v0, 16, v116
	v_fmac_f32_e32 v15, v28, v0
	v_and_b32_e32 v0, 0xffff0000, v114
	v_fmac_f32_e32 v15, v25, v0
	v_and_b32_e32 v0, 0xffff0000, v116
	v_fmac_f32_e32 v15, v29, v0
	v_lshlrev_b32_e32 v0, 16, v115
	v_fmac_f32_e32 v15, v26, v0
	v_lshlrev_b32_e32 v0, 16, v117
	v_fmac_f32_e32 v15, v30, v0
	v_and_b32_e32 v0, 0xffff0000, v115
	v_fmac_f32_e32 v15, v27, v0
	v_and_b32_e32 v0, 0xffff0000, v117
	v_fmac_f32_e32 v15, v31, v0
	s_waitcnt vmcnt(4)
	v_fmac_f32_e32 v15, v32, v17
	v_lshlrev_b32_e32 v0, 16, v120
	v_fmac_f32_e32 v15, v36, v0
	v_and_b32_e32 v0, 0xffff0000, v118
	v_fmac_f32_e32 v15, v33, v0
	v_and_b32_e32 v0, 0xffff0000, v120
	v_fmac_f32_e32 v15, v37, v0
	v_lshlrev_b32_e32 v0, 16, v119
	v_fmac_f32_e32 v15, v34, v0
	v_lshlrev_b32_e32 v0, 16, v121
	v_fmac_f32_e32 v15, v38, v0
	v_and_b32_e32 v0, 0xffff0000, v119
	v_fmac_f32_e32 v15, v35, v0
	v_and_b32_e32 v0, 0xffff0000, v121
	v_fmac_f32_e32 v15, v39, v0
	v_lshlrev_b32_e32 v17, 16, v122
	s_waitcnt vmcnt(2)
	v_fmac_f32_e32 v15, v40, v17
	v_lshlrev_b32_e32 v0, 16, v124
	v_fmac_f32_e32 v15, v44, v0
	v_and_b32_e32 v0, 0xffff0000, v122
	v_fmac_f32_e32 v15, v41, v0
	v_and_b32_e32 v0, 0xffff0000, v124
	v_fmac_f32_e32 v15, v45, v0
	v_lshlrev_b32_e32 v0, 16, v123
	v_fmac_f32_e32 v15, v42, v0
	v_lshlrev_b32_e32 v0, 16, v125
	v_fmac_f32_e32 v15, v46, v0
	v_and_b32_e32 v0, 0xffff0000, v123
	v_fmac_f32_e32 v15, v43, v0
	v_and_b32_e32 v0, 0xffff0000, v125
	v_fmac_f32_e32 v15, v47, v0
	v_lshlrev_b32_e32 v9, 16, v126
	v_lshlrev_b32_e32 v8, 16, v128
	s_waitcnt vmcnt(0)
	v_mov_b32_e32 v0, v130
	v_mov_b32_e32 v1, v131
	v_mov_b32_e32 v2, v132
	v_mov_b32_e32 v3, v133
	v_mov_b32_e32 v18, v134
	v_mov_b32_e32 v19, v135
	v_mov_b32_e32 v20, v136
	v_mov_b32_e32 v21, v137
	v_mov_b32_e32 v23, v0
	v_mov_b32_e32 v22, v18
	v_pk_mul_f32 v[8:9], v[22:23], v[8:9]
	s_nop 0
	v_add_f32_e32 v0, v9, v15
	v_add_f32_e32 v15, v8, v0
	v_and_b32_e32 v9, 0xffff0000, v126
	v_and_b32_e32 v8, 0xffff0000, v128
	v_mov_b32_e32 v0, v19
	v_pk_mul_f32 v[0:1], v[0:1], v[8:9]
	v_mov_b32_e32 v8, v20
	v_add_f32_e32 v1, v1, v15
	v_add_f32_e32 v15, v0, v1
	v_lshlrev_b32_e32 v1, 16, v127
	v_lshlrev_b32_e32 v0, 16, v129
	v_mov_b32_e32 v9, v2
	v_pk_mul_f32 v[0:1], v[8:9], v[0:1]
	v_mov_b32_e32 v2, v21
	v_add_f32_e32 v1, v1, v15
	v_add_f32_e32 v8, v0, v1
	v_and_b32_e32 v1, 0xffff0000, v127
	v_and_b32_e32 v0, 0xffff0000, v129
	v_pk_mul_f32 v[0:1], v[2:3], v[0:1]
	s_nop 0
	v_add_f32_e32 v1, v1, v8
	v_add_f32_e32 v0, v0, v1
	v_mov_b32_e32 v1, v0
	s_nop 1
	v_permlane32_swap_b32_e32 v0, v1
	v_add_f32_e32 v15, v0, v1
.LBB0_459:
	s_cmp_lt_u32 s2, 48
	s_cselect_b64 s[18:19], -1, 0
	s_cmp_gt_u32 s2, 47
	v_mov_b32_e32 v0, 0xff800000
	s_cbranch_scc1 .LBB0_461
	s_lshl_b32 s80, s3, 2
	v_lshl_add_u64 v[6:7], v[6:7], 0, s[80:81]
	global_load_dwordx4 v[24:27], v[6:7], off offset:1536
	global_load_dwordx4 v[28:31], v[6:7], off offset:1552
	global_load_dwordx4 v[32:35], v[6:7], off offset:1600
	global_load_dwordx4 v[36:39], v[6:7], off offset:1616
	global_load_dwordx4 v[40:43], v[6:7], off offset:1664
	global_load_dwordx4 v[44:47], v[6:7], off offset:1680
	global_load_dwordx4 v[130:133], v[6:7], off offset:1728
	global_load_dwordx4 v[134:137], v[6:7], off offset:1744
	s_waitcnt vmcnt(6) lgkmcnt(0)
	v_lshlrev_b32_e32 v8, 16, v114
	v_fma_f32 v17, v24, v8, 0
	v_lshlrev_b32_e32 v0, 16, v116
	v_fmac_f32_e32 v17, v28, v0
	v_and_b32_e32 v0, 0xffff0000, v114
	v_fmac_f32_e32 v17, v25, v0
	v_and_b32_e32 v0, 0xffff0000, v116
	v_fmac_f32_e32 v17, v29, v0
	v_lshlrev_b32_e32 v0, 16, v115
	v_fmac_f32_e32 v17, v26, v0
	v_lshlrev_b32_e32 v0, 16, v117
	v_fmac_f32_e32 v17, v30, v0
	v_and_b32_e32 v0, 0xffff0000, v115
	v_fmac_f32_e32 v17, v27, v0
	v_and_b32_e32 v0, 0xffff0000, v117
	v_fmac_f32_e32 v17, v31, v0
	v_lshlrev_b32_e32 v8, 16, v118
	s_waitcnt vmcnt(4)
	v_fmac_f32_e32 v17, v32, v8
	v_lshlrev_b32_e32 v0, 16, v120
	v_fmac_f32_e32 v17, v36, v0
	v_and_b32_e32 v0, 0xffff0000, v118
	v_fmac_f32_e32 v17, v33, v0
	v_and_b32_e32 v0, 0xffff0000, v120
	v_fmac_f32_e32 v17, v37, v0
	v_lshlrev_b32_e32 v0, 16, v119
	v_fmac_f32_e32 v17, v34, v0
	v_lshlrev_b32_e32 v0, 16, v121
	v_fmac_f32_e32 v17, v38, v0
	v_and_b32_e32 v0, 0xffff0000, v119
	v_fmac_f32_e32 v17, v35, v0
	v_and_b32_e32 v0, 0xffff0000, v121
	v_fmac_f32_e32 v17, v39, v0
	v_lshlrev_b32_e32 v8, 16, v122
	s_waitcnt vmcnt(2)
	v_fmac_f32_e32 v17, v40, v8
	v_lshlrev_b32_e32 v0, 16, v124
	v_fmac_f32_e32 v17, v44, v0
	v_and_b32_e32 v0, 0xffff0000, v122
	v_fmac_f32_e32 v17, v41, v0
	v_and_b32_e32 v0, 0xffff0000, v124
	v_fmac_f32_e32 v17, v45, v0
	v_lshlrev_b32_e32 v0, 16, v123
	v_fmac_f32_e32 v17, v42, v0
	v_lshlrev_b32_e32 v0, 16, v125
	v_fmac_f32_e32 v17, v46, v0
	v_and_b32_e32 v0, 0xffff0000, v123
	v_fmac_f32_e32 v17, v43, v0
	v_and_b32_e32 v0, 0xffff0000, v125
	v_fmac_f32_e32 v17, v47, v0
	s_nop 0
	v_lshlrev_b32_e32 v19, 16, v126
	v_lshlrev_b32_e32 v18, 16, v128
	s_waitcnt vmcnt(0)
	v_mov_b32_e32 v0, v130
	v_mov_b32_e32 v1, v131
	v_mov_b32_e32 v2, v132
	v_mov_b32_e32 v3, v133
	v_mov_b32_e32 v6, v134
	v_mov_b32_e32 v7, v135
	v_mov_b32_e32 v8, v136
	v_mov_b32_e32 v9, v137
	v_mov_b32_e32 v21, v0
	v_mov_b32_e32 v20, v6
	v_pk_mul_f32 v[18:19], v[20:21], v[18:19]
	s_nop 0
	v_add_f32_e32 v0, v19, v17
	v_add_f32_e32 v6, v18, v0
	v_and_b32_e32 v19, 0xffff0000, v126
	v_and_b32_e32 v18, 0xffff0000, v128
	v_mov_b32_e32 v0, v7
	v_pk_mul_f32 v[0:1], v[0:1], v[18:19]
	v_mov_b32_e32 v7, v2
	v_add_f32_e32 v1, v1, v6
	v_add_f32_e32 v17, v0, v1
	v_lshlrev_b32_e32 v1, 16, v127
	v_lshlrev_b32_e32 v0, 16, v129
	v_mov_b32_e32 v6, v8
	v_pk_mul_f32 v[0:1], v[6:7], v[0:1]
	v_mov_b32_e32 v2, v9
	v_add_f32_e32 v1, v1, v17
	v_add_f32_e32 v6, v0, v1
	v_and_b32_e32 v1, 0xffff0000, v127
	v_and_b32_e32 v0, 0xffff0000, v129
	v_pk_mul_f32 v[0:1], v[2:3], v[0:1]
	s_nop 0
	v_add_f32_e32 v1, v1, v6
	v_add_f32_e32 v0, v0, v1
	v_mov_b32_e32 v1, v0
	s_nop 1
	v_permlane32_swap_b32_e32 v0, v1
	v_add_f32_e32 v0, v0, v1
